# v121 + no workgroup barriers between the P2 inverse levels (column-local dependencies)
# speedup vs baseline: 1.0196x; 1.0030x over previous
; #define LAS __attribute__((address_space(3)))
; template <int SKIP>
; __device__ __forceinline__ void p2_chunk_prep_fast(Frame& F, const Args& a) {
;     ...
;         for (int dd = 1; dd < 4; ++dd) {
;             if (w < 4 - dd && !(SKIP & 8)) {
;                 const int bb = w, ab = w + dd;
;                 f32x4 acc = (f32x4){0.f, 0.f, 0.f, 0.f};
;                 for (int c = bb; c < ab; ++c)
; #pragma unroll
;                     for (int ks = 0; ks < 4; ++ks) acc = __builtin_amdgcn_mfma_f32_16x16x4f32(Am[(16 * ab + fr) * AM_LD + 16 * c + 4 * ks + fq], Tm[(16 * c + 4 * ks + fq) * AM_LD + 16 * bb + fr], acc, 0, 0, 0);
;                 LAS float* Xs = (LAS float*)(L + L_XS + w * 1152);
; #pragma unroll
;                 for (int r = 0; r < 4; ++r) Xs[(4 * fq + r) * 17 + fr] = acc[r];
;                 f32x4 acc2 = (f32x4){0.f, 0.f, 0.f, 0.f};
; #pragma unroll
;                 for (int ks = 0; ks < 4; ++ks) acc2 = __builtin_amdgcn_mfma_f32_16x16x4f32(Tm[(16 * ab + fr) * AM_LD + 16 * ab + 4 * ks + fq], Xs[(4 * ks + fq) * 17 + fr], acc2, 0, 0, 0);
; #pragma unroll
;                 for (int r = 0; r < 4; ++r) Tm[(16 * ab + 4 * fq + r) * AM_LD + 16 * bb + fr] = -acc2[r];
;             }
;             __syncthreads();
.LBB0_711:
	s_andn2_b64 vcc, exec, s[2:3]
	v_add_u32_e32 v49, s33, v118
	s_waitcnt lgkmcnt(0)
	s_cbranch_vccnz .Lkd_slot2
	v_or_b32_e32 v51, s10, v83
	v_mul_lo_u32 v58, v51, s28
	s_lshl_b32 s6, s54, 2
	v_add3_u32 v59, v47, v58, s6
	v_mad_u64_u32 v[56:57], s[6:7], v50, s28, v[46:47]
	v_mad_u64_u32 v[54:55], s[6:7], v49, s28, v[46:47]
	ds_read2_b32 v[152:153], v59 offset1:4
	ds_read2_b32 v[154:155], v59 offset0:8 offset1:12
	ds_read2_b32 v[156:157], v59 offset0:16 offset1:20
	ds_read2_b32 v[158:159], v59 offset0:24 offset1:28
	ds_read_b32 v160, v56
	ds_read_b32 v161, v56 offset:1088
	ds_read_b32 v162, v56 offset:2176
	ds_read_b32 v163, v56 offset:3264
	ds_read_b32 v164, v54
	ds_read_b32 v165, v54 offset:1088
	ds_read_b32 v166, v54 offset:2176
	ds_read_b32 v167, v54 offset:3264
	v_mad_u64_u32 v[60:61], s[6:7], v118, s28, v[48:49]
	s_lshl_b32 s6, s10, 2
	v_add_u32_e32 v55, s60, v58
	v_add3_u32 v62, v55, v67, s6
	s_movk_i32 s6, 0x44
	ds_read2_b32 v[168:169], v62 offset1:4
	ds_read2_b32 v[170:171], v62 offset0:8 offset1:12
	v_mad_u64_u32 v[56:57], s[6:7], v118, s6, v[48:49]
	s_waitcnt lgkmcnt(2)
	v_mfma_f32_16x16x4_f32 v[172:175], v152, v160, 0
	v_mfma_f32_16x16x4_f32 v[172:175], v153, v161, v[172:175]
	v_mfma_f32_16x16x4_f32 v[172:175], v154, v162, v[172:175]
	v_mfma_f32_16x16x4_f32 v[172:175], v155, v163, v[172:175]
	v_mfma_f32_16x16x4_f32 v[172:175], v156, v164, v[172:175]
	v_mfma_f32_16x16x4_f32 v[172:175], v157, v165, v[172:175]
	v_mfma_f32_16x16x4_f32 v[172:175], v158, v166, v[172:175]
	v_mfma_f32_16x16x4_f32 v[172:175], v159, v167, v[172:175]
	v_add_u32_e32 v54, s10, v67
	v_mad_u64_u32 v[54:55], s[6:7], v54, s28, v[46:47]
	s_nop 7
	ds_write2_b32 v60, v172, v173 offset1:17
	ds_write2_b32 v60, v174, v175 offset0:34 offset1:51
	ds_read2_b32 v[176:177], v56 offset1:68
	ds_read2_b32 v[178:179], v56 offset0:136 offset1:204
	s_waitcnt lgkmcnt(0)
	v_mfma_f32_16x16x4_f32 v[172:175], v168, v176, 0
	v_mfma_f32_16x16x4_f32 v[172:175], v169, v177, v[172:175]
	v_mfma_f32_16x16x4_f32 v[172:175], v170, v178, v[172:175]
	v_mfma_f32_16x16x4_f32 v[172:175], v171, v179, v[172:175]
	s_nop 9
	v_xor_b32_e32 v50, 0x80000000, v172
	v_xor_b32_e32 v51, 0x80000000, v173
	v_xor_b32_e32 v52, 0x80000000, v174
	v_xor_b32_e32 v53, 0x80000000, v175
	ds_write2_b32 v54, v50, v51 offset1:68
	ds_write2_b32 v54, v52, v53 offset0:136 offset1:204
	s_branch .LBB0_713

; #define LAS __attribute__((address_space(3)))
; template <int SKIP>
; __device__ __forceinline__ void p2_chunk_prep_fast(Frame& F, const Args& a) {
;     ...
;         for (int dd = 1; dd < 4; ++dd) {
;             if (w < 4 - dd && !(SKIP & 8)) {
;                 const int bb = w, ab = w + dd;
;                 f32x4 acc = (f32x4){0.f, 0.f, 0.f, 0.f};
;                 for (int c = bb; c < ab; ++c)
; #pragma unroll
;                     for (int ks = 0; ks < 4; ++ks) acc = __builtin_amdgcn_mfma_f32_16x16x4f32(Am[(16 * ab + fr) * AM_LD + 16 * c + 4 * ks + fq], Tm[(16 * c + 4 * ks + fq) * AM_LD + 16 * bb + fr], acc, 0, 0, 0);
;                 LAS float* Xs = (LAS float*)(L + L_XS + w * 1152);
; #pragma unroll
;                 for (int r = 0; r < 4; ++r) Xs[(4 * fq + r) * 17 + fr] = acc[r];
;                 f32x4 acc2 = (f32x4){0.f, 0.f, 0.f, 0.f};
; #pragma unroll
;                 for (int ks = 0; ks < 4; ++ks) acc2 = __builtin_amdgcn_mfma_f32_16x16x4f32(Tm[(16 * ab + fr) * AM_LD + 16 * ab + 4 * ks + fq], Xs[(4 * ks + fq) * 17 + fr], acc2, 0, 0, 0);
; #pragma unroll
;                 for (int r = 0; r < 4; ++r) Tm[(16 * ab + 4 * fq + r) * AM_LD + 16 * bb + fr] = -acc2[r];
;             }
;             __syncthreads();
.LBB0_713:
	s_andn2_b64 vcc, exec, s[50:51]
	s_waitcnt lgkmcnt(0)
	s_cbranch_vccnz .Lkd_slot3
	v_mul_u32_u24_e32 v58, 0x110, v83
	s_lshl_b32 s6, s54, 2
	v_add3_u32 v47, v47, v58, s6
	v_add_u32_e32 v47, 0x3000, v47
	v_mul_lo_u32 v59, v118, s28
	v_add_u32_e32 v56, v46, v59
	v_mad_u64_u32 v[54:55], s[6:7], v49, s28, v[46:47]
	v_add_u32_e32 v60, s10, v118
	v_mad_u64_u32 v[60:61], s[6:7], v60, s28, v[46:47]
	ds_read2_b32 v[152:153], v47 offset0:192 offset1:196
	ds_read2_b32 v[154:155], v47 offset0:200 offset1:204
	ds_read2_b32 v[156:157], v47 offset0:208 offset1:212
	ds_read2_b32 v[158:159], v47 offset0:216 offset1:220
	ds_read2_b32 v[160:161], v47 offset0:224 offset1:228
	ds_read2_b32 v[162:163], v47 offset0:232 offset1:236
	ds_read_b32 v164, v56
	ds_read_b32 v165, v56 offset:1088
	ds_read_b32 v166, v56 offset:2176
	ds_read_b32 v167, v56 offset:3264
	ds_read_b32 v168, v54
	ds_read_b32 v169, v54 offset:1088
	ds_read_b32 v170, v54 offset:2176
	ds_read_b32 v171, v54 offset:3264
	ds_read_b32 v172, v60
	ds_read_b32 v173, v60 offset:1088
	ds_read_b32 v174, v60 offset:2176
	ds_read_b32 v175, v60 offset:3264
	v_readlane_b32 s6, v255, 53
	v_add_u32_e32 v49, v48, v59
	s_nop 1
	v_add3_u32 v62, s6, v58, v67
	v_add_u32_e32 v62, 0x3000, v62
	ds_read2_b32 v[176:177], v62 offset0:192 offset1:196
	ds_read2_b32 v[178:179], v62 offset0:200 offset1:204
	s_movk_i32 s6, 0x44
	v_mad_u64_u32 v[54:55], s[6:7], v118, s6, v[48:49]
	s_waitcnt lgkmcnt(2)
	v_mfma_f32_16x16x4_f32 v[180:183], v152, v164, 0
	v_mfma_f32_16x16x4_f32 v[180:183], v153, v165, v[180:183]
	v_mfma_f32_16x16x4_f32 v[180:183], v154, v166, v[180:183]
	v_mfma_f32_16x16x4_f32 v[180:183], v155, v167, v[180:183]
	v_mfma_f32_16x16x4_f32 v[180:183], v156, v168, v[180:183]
	v_mfma_f32_16x16x4_f32 v[180:183], v157, v169, v[180:183]
	v_mfma_f32_16x16x4_f32 v[180:183], v158, v170, v[180:183]
	v_mfma_f32_16x16x4_f32 v[180:183], v159, v171, v[180:183]
	v_mfma_f32_16x16x4_f32 v[180:183], v160, v172, v[180:183]
	v_mfma_f32_16x16x4_f32 v[180:183], v161, v173, v[180:183]
	v_mfma_f32_16x16x4_f32 v[180:183], v162, v174, v[180:183]
	v_mfma_f32_16x16x4_f32 v[180:183], v163, v175, v[180:183]
	v_readlane_b32 s6, v255, 51
	s_nop 1
	v_add_u32_e32 v47, s6, v67
	v_mad_u64_u32 v[46:47], s[6:7], v47, s28, v[46:47]
	s_nop 4
	ds_write2_b32 v49, v180, v181 offset1:17
	ds_write2_b32 v49, v182, v183 offset0:34 offset1:51
	ds_read2_b32 v[184:185], v54 offset1:68
	ds_read2_b32 v[186:187], v54 offset0:136 offset1:204
	s_waitcnt lgkmcnt(0)
	v_mfma_f32_16x16x4_f32 v[180:183], v176, v184, 0
	v_mfma_f32_16x16x4_f32 v[180:183], v177, v185, v[180:183]
	v_mfma_f32_16x16x4_f32 v[180:183], v178, v186, v[180:183]
	v_mfma_f32_16x16x4_f32 v[180:183], v179, v187, v[180:183]
	s_nop 9
	v_xor_b32_e32 v188, 0x80000000, v180
	v_xor_b32_e32 v189, 0x80000000, v181
	v_xor_b32_e32 v190, 0x80000000, v182
	v_xor_b32_e32 v191, 0x80000000, v183
	ds_write2_b32 v46, v188, v189 offset1:68
	ds_write2_b32 v46, v190, v191 offset0:136 offset1:204
	s_branch .LBB0_715
